# k0 X segment: tile-offset scalar math before the staged-tile wait, wait + LDS writes one MFMA slot later so the next loads issue 3 slots after the wait (was 4); rest as v67
# baseline (speedup 1.0000x reference)
; template <int DV> ...
;     ...
;         const int k0 = (t < n0) ? (s0a + (t << 6)) : (s1a + ((t - n0) << 6));
;         const bool more = (t + 1 < nt);
;         if (more) {
;             const int k1 = (t + 1 < n0) ? (s0a + ((t + 1) << 6)) : (s1a + ((t + 1 - n0) << 6));
;             kr = *(const u32x4*)(kg + (size_t)k1 * kpitch); vr0 = *(const u32x4*)(vg + k1);
;             if (DV == 128) vr1 = *(const u32x4*)(vg + (size_t)64 * NKV + k1);
;         }
;         const LAS unsigned char* Kl = lds + (t & 1) * ABUFB;
;         const LAS unsigned char* Vl = Kl + KBUFB;
;         const bool masked = win && (t < n0);
;         const bool skip = masked && ((k0 + 63 < qw0 - 128) || (k0 > qw0 + 31 + 128));
;         if (!skip) {
;             f32x16 p0, p1;
;             {
;                 bf16x8 kf[8];
; #pragma unroll
;                 for (int d0 = 0; d0 < 4; ++d0) {
;                     kf[2 * d0] = *(const LAS bf16x8*)(Kl + (r32 * KP + 16 * d0 + 8 * hi) * 2);
;                     kf[2 * d0 + 1] = *(const LAS bf16x8*)(Kl + ((32 + r32) * KP + 16 * d0 + 8 * hi) * 2);
;                 }
;                 __builtin_amdgcn_sched_barrier(0);
;                 p0 = __builtin_amdgcn_mfma_f32_32x32x16_bf16(kf[0], qf[0], negm, 0, 0, 0); p1 = __builtin_amdgcn_mfma_f32_32x32x16_bf16(kf[1], qf[0], negm, 0, 0, 0);
; #pragma unroll
;                 for (int d0 = 1; d0 < 4; ++d0) { p0 = __builtin_amdgcn_mfma_f32_32x32x16_bf16(kf[2 * d0], qf[d0], p0, 0, 0, 0); p1 = __builtin_amdgcn_mfma_f32_32x32x16_bf16(kf[2 * d0 + 1], qf[d0], p1, 0, 0, 0); }
;                 __builtin_amdgcn_sched_barrier(0);
;             }
;     ...
; #pragma unroll
;                 for (int db = 0; db < 2; ++db)
; #pragma unroll
;                     for (int c = 0; c < 4; ++c) {
;                         o[db] = __builtin_amdgcn_mfma_f32_32x32x16_bf16(vfa[db * 4 + c], pk[c], o[db], 0, 0, 0);
;                     }
;                 __builtin_amdgcn_sched_barrier(0);
; #pragma unroll
;                 for (int db = 2; db < DV / 32; ++db)
; #pragma unroll
;                     for (int c = 0; c < 4; ++c) {
;                         o[db] = __builtin_amdgcn_mfma_f32_32x32x16_bf16(vfb[(db - 2) * 4 + c], pk[c], o[db], 0, 0, 0);
;                     }
;             } else {
; #pragma unroll
;                 for (int db = 0; db < 2; ++db)
; #pragma unroll
;                     for (int c = 0; c < 4; ++c) {
.Lpa_X2:
	s_setprio 1
	s_cmp_ge_i32 s22, s26
	s_cbranch_scc1 .Lpa_Xlast
	s_waitcnt lgkmcnt(11)
	v_mfma_f32_32x32x16_bf16 v[2:17], v[82:85], v[200:203], v[2:17]
	ds_read_b128 v[158:161], v197 offset:23040
	s_waitcnt lgkmcnt(11)
	v_mfma_f32_32x32x16_bf16 v[2:17], v[86:89], v[204:207], v[2:17]
	ds_read_b128 v[162:165], v197 offset:23072
	s_waitcnt lgkmcnt(11)
	v_mfma_f32_32x32x16_bf16 v[2:17], v[90:93], v[210:213], v[2:17]
	ds_read_b128 v[166:169], v197 offset:23104
	s_waitcnt lgkmcnt(11)
	v_mfma_f32_32x32x16_bf16 v[2:17], v[94:97], v[214:217], v[2:17]
	ds_read_b128 v[170:173], v197 offset:23136
	s_waitcnt lgkmcnt(11)
	v_mfma_f32_32x32x16_bf16 v[18:33], v[98:101], v[200:203], v[18:33]
	s_add_i32 s3, s22, 2
	s_add_i32 s4, s26, -1
	s_min_i32 s3, s3, s4
	s_cmp_lt_i32 s3, s1
	s_cselect_b32 s4, 0, s1
	s_cselect_b32 s5, s94, 0x2000
	s_sub_i32 s4, s3, s4
	s_lshl_b32 s4, s4, 6
	s_add_i32 s4, s5, s4
	s_ashr_i32 s5, s4, 31
	s_waitcnt vmcnt(0)
	s_waitcnt lgkmcnt(11)
	v_mfma_f32_32x32x16_bf16 v[18:33], v[102:105], v[204:207], v[18:33]
	ds_write_b128 v218, v[130:133]
	s_waitcnt lgkmcnt(11)
	v_mfma_f32_32x32x16_bf16 v[18:33], v[106:109], v[210:213], v[18:33]
	ds_write_b128 v219, v[134:137] offset:9216
	s_waitcnt lgkmcnt(11)
	v_mfma_f32_32x32x16_bf16 v[18:33], v[110:113], v[214:217], v[18:33]
	ds_write_b128 v219, v[138:141] offset:18432
	s_lshl_b64 s[30:31], s[4:5], 10
	v_lshl_add_u64 v[218:219], v[180:181], 0, s[30:31]
	s_lshl_b64 s[30:31], s[4:5], 1
	v_lshl_add_u64 v[220:221], v[182:183], 0, s[30:31]
	s_waitcnt lgkmcnt(10)
	v_mfma_f32_32x32x16_bf16 v[50:65], v[142:145], v[200:203], v[50:65]
	ds_read_b128 v[142:145], v199
	global_load_dwordx4 v[130:133], v[218:219], off
	s_waitcnt lgkmcnt(10)
	v_mfma_f32_32x32x16_bf16 v[50:65], v[146:149], v[204:207], v[50:65]
	ds_read_b128 v[146:149], v199 offset:4608
	global_load_dwordx4 v[134:137], v[220:221], off
	s_waitcnt lgkmcnt(10)
	v_mfma_f32_32x32x16_bf16 v[50:65], v[150:153], v[210:213], v[50:65]
	ds_read_b128 v[150:153], v199 offset:32
	v_lshl_add_u64 v[218:219], v[186:187], 0, s[30:31]
	s_waitcnt lgkmcnt(10)
	v_mfma_f32_32x32x16_bf16 v[50:65], v[154:157], v[214:217], v[50:65]
	ds_read_b128 v[154:157], v199 offset:4640
	global_load_dwordx4 v[138:141], v[218:219], off
	s_waitcnt lgkmcnt(10)
	v_mfma_f32_32x32x16_bf16 v[34:49], v[158:161], v[200:203], v[34:49]
	ds_read_b128 v[158:161], v199 offset:64
	s_waitcnt lgkmcnt(10)
	v_mfma_f32_32x32x16_bf16 v[34:49], v[162:165], v[204:207], v[34:49]
	ds_read_b128 v[162:165], v199 offset:4672
	s_waitcnt lgkmcnt(10)
	v_mfma_f32_32x32x16_bf16 v[34:49], v[166:169], v[210:213], v[34:49]
	ds_read_b128 v[166:169], v199 offset:96
	s_waitcnt lgkmcnt(10)
	v_mfma_f32_32x32x16_bf16 v[34:49], v[170:173], v[214:217], v[34:49]
	ds_read_b128 v[170:173], v199 offset:4704
	s_waitcnt lgkmcnt(7)
	v_mfma_f32_32x32x16_bf16 v[98:113], v[142:145], v[126:129], v[66:81]
	s_waitcnt lgkmcnt(5)
	v_mfma_f32_32x32x16_bf16 v[98:113], v[150:153], v[122:125], v[98:113]
	s_waitcnt lgkmcnt(3)
	v_mfma_f32_32x32x16_bf16 v[98:113], v[158:161], v[118:121], v[98:113]
	s_waitcnt lgkmcnt(1)
	v_mfma_f32_32x32x16_bf16 v[98:113], v[166:169], v[114:117], v[98:113]
	v_mfma_f32_32x32x16_bf16 v[82:97], v[146:149], v[126:129], v[66:81]
	v_mfma_f32_32x32x16_bf16 v[82:97], v[154:157], v[122:125], v[82:97]
	v_mfma_f32_32x32x16_bf16 v[82:97], v[162:165], v[118:121], v[82:97]
	s_waitcnt lgkmcnt(0)
	v_mfma_f32_32x32x16_bf16 v[82:97], v[170:173], v[114:117], v[82:97]
	s_cmp_eq_u32 s25, 0
	s_cbranch_scc1 .Lpa_Y
	s_barrier
